# grid barrier spin loops: s_sleep 1 between polls removed
# baseline (speedup 1.0000x reference)
.Lgs_88:
	s_mov_b64 s[10:11], -1
	s_waitcnt lgkmcnt(0)
	global_load_dword v2, v157, s[50:51] offset:0 sc1
	global_load_dword v0, v157, s[50:51] offset:256 sc1
	global_load_dword v1, v157, s[50:51] offset:512 sc1
	global_load_dword v3, v157, s[50:51] offset:768 sc1
	global_load_dword v4, v157, s[50:51] offset:1024 sc1
	global_load_dword v5, v157, s[50:51] offset:1280 sc1
	global_load_dword v6, v157, s[50:51] offset:1536 sc1
	global_load_dword v7, v157, s[50:51] offset:1792 sc1
	global_load_dword v8, v157, s[50:51] offset:2048 sc1
	global_load_dword v9, v157, s[50:51] offset:2304 sc1
	global_load_dword v10, v157, s[50:51] offset:2560 sc1
	global_load_dword v11, v157, s[50:51] offset:2816 sc1
	global_load_dword v12, v157, s[50:51] offset:3072 sc1
	global_load_dword v13, v157, s[50:51] offset:3328 sc1
	global_load_dword v14, v157, s[50:51] offset:3584 sc1
	global_load_dword v15, v157, s[50:51] offset:3840 sc1
	s_mov_b64 s[8:9], -1
	s_waitcnt vmcnt(0)
	v_add3_u32 v16, v0, v2, v1
	v_add3_u32 v16, v16, v3, v4
	v_add3_u32 v16, v16, v5, v6
	v_add3_u32 v16, v16, v7, v8
	v_add3_u32 v16, v16, v9, v10
	v_add3_u32 v16, v16, v11, v12
	v_add3_u32 v16, v16, v13, v14
	v_add_u32_e32 v16, v16, v15
	v_cmp_eq_u32_e32 vcc, s62, v16
	s_cbranch_vccnz .Lgs_87
	s_and_b32 s8, s14, 0xff
	s_cmp_eq_u32 s8, 0
	s_mov_b64 s[8:9], -1
	s_mov_b64 s[12:13], -1
	s_nop 0
	s_cbranch_scc0 .Lgs_92
	global_load_dword v16, v157, s[88:89] sc1
	s_waitcnt vmcnt(0)
	v_cmp_eq_u32_e32 vcc, 0, v16
	s_cbranch_vccnz .Lgs_94
	s_mov_b64 s[12:13], 0

.Lgs_106:
	s_and_b32 s18, s40, 0xff
	s_mov_b64 s[16:17], -1
	s_cmp_lg_u32 s18, 0
	s_mov_b64 s[22:23], -1
	s_nop 0
	s_cbranch_scc1 .Lgs_109
	global_load_dword v0, v157, s[88:89] sc1
	s_waitcnt vmcnt(0)
	v_cmp_eq_u32_e32 vcc, 0, v0
	s_cbranch_vccnz .Lgs_111
	s_mov_b64 s[22:23], 0
	s_mov_b64 s[18:19], -1

.LBB0_88:
	v_readlane_b32 s8, v249, 51
	v_readlane_b32 s9, v249, 52
	global_load_dword v2, v157, s[50:51] sc1
	s_waitcnt lgkmcnt(0)
	global_load_dword v0, v157, s[48:49] sc1
	global_load_dword v1, v157, s[52:53] sc1
	s_mov_b64 s[10:11], -1
	s_waitcnt vmcnt(1)
	v_add_u32_e32 v16, v0, v2
	global_load_dword v3, v157, s[8:9] sc1
	v_readlane_b32 s8, v249, 53
	v_readlane_b32 s9, v249, 54
	s_waitcnt vmcnt(1)
	v_add_u32_e32 v16, v16, v1
	s_waitcnt vmcnt(0)
	v_add_u32_e32 v16, v16, v3
	s_nop 0
	global_load_dword v4, v157, s[8:9] sc1
	v_readlane_b32 s8, v249, 55
	v_readlane_b32 s9, v249, 56
	s_waitcnt vmcnt(0)
	v_add_u32_e32 v16, v16, v4
	s_nop 2
	global_load_dword v5, v157, s[8:9] sc1
	v_readlane_b32 s8, v249, 57
	v_readlane_b32 s9, v249, 58
	s_waitcnt vmcnt(0)
	v_add_u32_e32 v16, v16, v5
	s_nop 2
	global_load_dword v6, v157, s[8:9] sc1
	v_readlane_b32 s8, v249, 59
	v_readlane_b32 s9, v249, 60
	s_waitcnt vmcnt(0)
	v_add_u32_e32 v16, v16, v6
	s_nop 2
	global_load_dword v7, v157, s[8:9] sc1
	v_readlane_b32 s8, v249, 61
	v_readlane_b32 s9, v249, 62
	s_waitcnt vmcnt(0)
	v_add_u32_e32 v16, v16, v7
	s_nop 2
	global_load_dword v8, v157, s[8:9] sc1
	v_readlane_b32 s8, v249, 63
	v_readlane_b32 s9, v250, 0
	s_waitcnt vmcnt(0)
	v_add_u32_e32 v16, v16, v8
	s_nop 2
	global_load_dword v9, v157, s[8:9] sc1
	v_readlane_b32 s8, v250, 1
	v_readlane_b32 s9, v250, 2
	s_waitcnt vmcnt(0)
	v_add_u32_e32 v16, v16, v9
	s_nop 2
	global_load_dword v10, v157, s[8:9] sc1
	v_readlane_b32 s8, v250, 3
	v_readlane_b32 s9, v250, 4
	s_waitcnt vmcnt(0)
	v_add_u32_e32 v16, v16, v10
	s_nop 2
	global_load_dword v11, v157, s[8:9] sc1
	v_readlane_b32 s8, v250, 5
	v_readlane_b32 s9, v250, 6
	s_waitcnt vmcnt(0)
	v_add_u32_e32 v16, v16, v11
	s_nop 2
	global_load_dword v12, v157, s[8:9] sc1
	v_readlane_b32 s8, v250, 7
	v_readlane_b32 s9, v250, 8
	s_waitcnt vmcnt(0)
	v_add_u32_e32 v16, v16, v12
	s_nop 2
	global_load_dword v13, v157, s[8:9] sc1
	v_readlane_b32 s8, v250, 9
	v_readlane_b32 s9, v250, 10
	s_nop 4
	global_load_dword v14, v157, s[8:9] sc1
	global_load_dword v15, v157, s[84:85] sc1
	s_mov_b64 s[8:9], -1
	s_waitcnt vmcnt(2)
	v_add_u32_e32 v16, v16, v13
	s_waitcnt vmcnt(1)
	v_add_u32_e32 v16, v16, v14
	s_waitcnt vmcnt(0)
	v_add_u32_e32 v16, v16, v15
	v_cmp_eq_u32_e32 vcc, s62, v16
	s_cbranch_vccnz .LBB0_87
	s_and_b32 s8, s14, 0xff
	s_cmp_eq_u32 s8, 0
	s_mov_b64 s[8:9], -1
	s_mov_b64 s[12:13], -1
	s_nop 0
	s_cbranch_scc0 .LBB0_92
	global_load_dword v16, v157, s[88:89] sc1
	s_waitcnt vmcnt(0)
	v_cmp_eq_u32_e32 vcc, 0, v16
	s_cbranch_vccnz .LBB0_94
	s_mov_b64 s[12:13], 0

.LBB0_156:
	v_readlane_b32 s4, v249, 51
	v_readlane_b32 s5, v249, 52
	global_load_dword v2, v157, s[50:51] sc1
	s_waitcnt lgkmcnt(0)
	global_load_dword v0, v157, s[48:49] sc1
	global_load_dword v1, v157, s[52:53] sc1
	s_mov_b64 s[8:9], -1
	s_waitcnt vmcnt(1)
	v_add_u32_e32 v16, v0, v2
	global_load_dword v3, v157, s[4:5] sc1
	v_readlane_b32 s4, v249, 53
	v_readlane_b32 s5, v249, 54
	s_waitcnt vmcnt(1)
	v_add_u32_e32 v16, v16, v1
	s_waitcnt vmcnt(0)
	v_add_u32_e32 v16, v16, v3
	s_nop 0
	global_load_dword v4, v157, s[4:5] sc1
	v_readlane_b32 s4, v249, 55
	v_readlane_b32 s5, v249, 56
	s_waitcnt vmcnt(0)
	v_add_u32_e32 v16, v16, v4
	s_nop 2
	global_load_dword v5, v157, s[4:5] sc1
	v_readlane_b32 s4, v249, 57
	v_readlane_b32 s5, v249, 58
	s_waitcnt vmcnt(0)
	v_add_u32_e32 v16, v16, v5
	s_nop 2
	global_load_dword v6, v157, s[4:5] sc1
	v_readlane_b32 s4, v249, 59
	v_readlane_b32 s5, v249, 60
	s_waitcnt vmcnt(0)
	v_add_u32_e32 v16, v16, v6
	s_nop 2
	global_load_dword v7, v157, s[4:5] sc1
	v_readlane_b32 s4, v249, 61
	v_readlane_b32 s5, v249, 62
	s_waitcnt vmcnt(0)
	v_add_u32_e32 v16, v16, v7
	s_nop 2
	global_load_dword v8, v157, s[4:5] sc1
	v_readlane_b32 s4, v249, 63
	v_readlane_b32 s5, v250, 0
	s_waitcnt vmcnt(0)
	v_add_u32_e32 v16, v16, v8
	s_nop 2
	global_load_dword v9, v157, s[4:5] sc1
	v_readlane_b32 s4, v250, 1
	v_readlane_b32 s5, v250, 2
	s_waitcnt vmcnt(0)
	v_add_u32_e32 v16, v16, v9
	s_nop 2
	global_load_dword v10, v157, s[4:5] sc1
	v_readlane_b32 s4, v250, 3
	v_readlane_b32 s5, v250, 4
	s_waitcnt vmcnt(0)
	v_add_u32_e32 v16, v16, v10
	s_nop 2
	global_load_dword v11, v157, s[4:5] sc1
	v_readlane_b32 s4, v250, 5
	v_readlane_b32 s5, v250, 6
	s_waitcnt vmcnt(0)
	v_add_u32_e32 v16, v16, v11
	s_nop 2
	global_load_dword v12, v157, s[4:5] sc1
	v_readlane_b32 s4, v250, 7
	v_readlane_b32 s5, v250, 8
	s_waitcnt vmcnt(0)
	v_add_u32_e32 v16, v16, v12
	s_nop 2
	global_load_dword v13, v157, s[4:5] sc1
	v_readlane_b32 s4, v250, 9
	v_readlane_b32 s5, v250, 10
	s_nop 4
	global_load_dword v14, v157, s[4:5] sc1
	global_load_dword v15, v157, s[84:85] sc1
	s_mov_b64 s[4:5], -1
	s_waitcnt vmcnt(2)
	v_add_u32_e32 v16, v16, v13
	s_waitcnt vmcnt(1)
	v_add_u32_e32 v16, v16, v14
	s_waitcnt vmcnt(0)
	v_add_u32_e32 v16, v16, v15
	v_cmp_eq_u32_e32 vcc, s62, v16
	s_cbranch_vccnz .LBB0_155
	s_and_b32 s4, s12, 0xff
	s_cmp_eq_u32 s4, 0
	s_mov_b64 s[4:5], -1
	s_mov_b64 s[10:11], -1
	s_nop 0
	s_cbranch_scc0 .LBB0_160
	global_load_dword v16, v157, s[88:89] sc1
	s_waitcnt vmcnt(0)
	v_cmp_eq_u32_e32 vcc, 0, v16
	s_cbranch_vccnz .LBB0_162
	s_mov_b64 s[10:11], 0

.LBB0_174:
	s_and_b32 s16, s22, 0xff
	s_mov_b64 s[14:15], -1
	s_cmp_lg_u32 s16, 0
	s_mov_b64 s[18:19], -1
	s_nop 0
	s_cbranch_scc1 .LBB0_177
	global_load_dword v0, v157, s[88:89] sc1
	s_waitcnt vmcnt(0)
	v_cmp_eq_u32_e32 vcc, 0, v0
	s_cbranch_vccnz .LBB0_179
	s_mov_b64 s[18:19], 0
	s_mov_b64 s[16:17], -1

.LBB0_232:
	v_readlane_b32 s4, v249, 51
	v_readlane_b32 s5, v249, 52
	global_load_dword v2, v157, s[50:51] sc1
	s_waitcnt lgkmcnt(0)
	global_load_dword v0, v157, s[48:49] sc1
	global_load_dword v1, v157, s[52:53] sc1
	s_mov_b64 s[6:7], -1
	s_waitcnt vmcnt(1)
	v_add_u32_e32 v16, v0, v2
	global_load_dword v3, v157, s[4:5] sc1
	v_readlane_b32 s4, v249, 53
	v_readlane_b32 s5, v249, 54
	s_waitcnt vmcnt(1)
	v_add_u32_e32 v16, v16, v1
	s_waitcnt vmcnt(0)
	v_add_u32_e32 v16, v16, v3
	s_nop 0
	global_load_dword v4, v157, s[4:5] sc1
	v_readlane_b32 s4, v249, 55
	v_readlane_b32 s5, v249, 56
	s_waitcnt vmcnt(0)
	v_add_u32_e32 v16, v16, v4
	s_nop 2
	global_load_dword v5, v157, s[4:5] sc1
	v_readlane_b32 s4, v249, 57
	v_readlane_b32 s5, v249, 58
	s_waitcnt vmcnt(0)
	v_add_u32_e32 v16, v16, v5
	s_nop 2
	global_load_dword v6, v157, s[4:5] sc1
	v_readlane_b32 s4, v249, 59
	v_readlane_b32 s5, v249, 60
	s_waitcnt vmcnt(0)
	v_add_u32_e32 v16, v16, v6
	s_nop 2
	global_load_dword v7, v157, s[4:5] sc1
	v_readlane_b32 s4, v249, 61
	v_readlane_b32 s5, v249, 62
	s_waitcnt vmcnt(0)
	v_add_u32_e32 v16, v16, v7
	s_nop 2
	global_load_dword v8, v157, s[4:5] sc1
	v_readlane_b32 s4, v249, 63
	v_readlane_b32 s5, v250, 0
	s_waitcnt vmcnt(0)
	v_add_u32_e32 v16, v16, v8
	s_nop 2
	global_load_dword v9, v157, s[4:5] sc1
	v_readlane_b32 s4, v250, 1
	v_readlane_b32 s5, v250, 2
	s_waitcnt vmcnt(0)
	v_add_u32_e32 v16, v16, v9
	s_nop 2
	global_load_dword v10, v157, s[4:5] sc1
	v_readlane_b32 s4, v250, 3
	v_readlane_b32 s5, v250, 4
	s_waitcnt vmcnt(0)
	v_add_u32_e32 v16, v16, v10
	s_nop 2
	global_load_dword v11, v157, s[4:5] sc1
	v_readlane_b32 s4, v250, 5
	v_readlane_b32 s5, v250, 6
	s_waitcnt vmcnt(0)
	v_add_u32_e32 v16, v16, v11
	s_nop 2
	global_load_dword v12, v157, s[4:5] sc1
	v_readlane_b32 s4, v250, 7
	v_readlane_b32 s5, v250, 8
	s_waitcnt vmcnt(0)
	v_add_u32_e32 v16, v16, v12
	s_nop 2
	global_load_dword v13, v157, s[4:5] sc1
	v_readlane_b32 s4, v250, 9
	v_readlane_b32 s5, v250, 10
	s_nop 4
	global_load_dword v14, v157, s[4:5] sc1
	global_load_dword v15, v157, s[84:85] sc1
	s_mov_b64 s[4:5], -1
	s_waitcnt vmcnt(2)
	v_add_u32_e32 v16, v16, v13
	s_waitcnt vmcnt(1)
	v_add_u32_e32 v16, v16, v14
	s_waitcnt vmcnt(0)
	v_add_u32_e32 v16, v16, v15
	v_cmp_eq_u32_e32 vcc, s62, v16
	s_cbranch_vccnz .LBB0_231
	s_and_b32 s4, s10, 0xff
	s_cmp_eq_u32 s4, 0
	s_mov_b64 s[4:5], -1
	s_mov_b64 s[8:9], -1
	s_nop 0
	s_cbranch_scc0 .LBB0_236
	global_load_dword v16, v157, s[88:89] sc1
	s_waitcnt vmcnt(0)
	v_cmp_eq_u32_e32 vcc, 0, v16
	s_cbranch_vccnz .LBB0_238
	s_mov_b64 s[8:9], 0

.LBB0_250:
	s_and_b32 s14, s18, 0xff
	s_mov_b64 s[12:13], -1
	s_cmp_lg_u32 s14, 0
	s_mov_b64 s[16:17], -1
	s_nop 0
	s_cbranch_scc1 .LBB0_253
	global_load_dword v0, v157, s[88:89] sc1
	s_waitcnt vmcnt(0)
	v_cmp_eq_u32_e32 vcc, 0, v0
	s_cbranch_vccnz .LBB0_255
	s_mov_b64 s[16:17], 0
	s_mov_b64 s[14:15], -1

.LBB0_372:
	v_readlane_b32 s4, v249, 53
	v_readlane_b32 s5, v249, 54
	global_load_dword v3, v157, s[50:51] sc1
	s_waitcnt lgkmcnt(0)
	global_load_dword v0, v157, s[48:49] sc1
	global_load_dword v1, v157, s[52:53] sc1
	global_load_dword v2, v157, s[22:23] sc1
	s_mov_b64 s[6:7], -1
	global_load_dword v4, v157, s[4:5] sc1
	v_readlane_b32 s4, v249, 55
	v_readlane_b32 s5, v249, 56
	s_waitcnt vmcnt(3)
	v_add_u32_e32 v16, v0, v3
	s_nop 2
	global_load_dword v5, v157, s[4:5] sc1
	v_readlane_b32 s4, v249, 57
	v_readlane_b32 s5, v249, 58
	s_waitcnt vmcnt(3)
	v_add_u32_e32 v16, v16, v1
	s_waitcnt vmcnt(2)
	v_add_u32_e32 v16, v16, v2
	s_waitcnt vmcnt(1)
	v_add_u32_e32 v16, v16, v4
	s_waitcnt vmcnt(0)
	v_add_u32_e32 v16, v16, v5
	global_load_dword v6, v157, s[4:5] sc1
	v_readlane_b32 s4, v249, 59
	v_readlane_b32 s5, v249, 60
	s_waitcnt vmcnt(0)
	v_add_u32_e32 v16, v16, v6
	s_nop 2
	global_load_dword v7, v157, s[4:5] sc1
	v_readlane_b32 s4, v249, 61
	v_readlane_b32 s5, v249, 62
	s_waitcnt vmcnt(0)
	v_add_u32_e32 v16, v16, v7
	s_nop 2
	global_load_dword v8, v157, s[4:5] sc1
	v_readlane_b32 s4, v249, 63
	v_readlane_b32 s5, v250, 0
	s_waitcnt vmcnt(0)
	v_add_u32_e32 v16, v16, v8
	s_nop 2
	global_load_dword v9, v157, s[4:5] sc1
	v_readlane_b32 s4, v250, 1
	v_readlane_b32 s5, v250, 2
	s_waitcnt vmcnt(0)
	v_add_u32_e32 v16, v16, v9
	s_nop 2
	global_load_dword v10, v157, s[4:5] sc1
	v_readlane_b32 s4, v250, 3
	v_readlane_b32 s5, v250, 4
	s_waitcnt vmcnt(0)
	v_add_u32_e32 v16, v16, v10
	s_nop 2
	global_load_dword v11, v157, s[4:5] sc1
	v_readlane_b32 s4, v250, 5
	v_readlane_b32 s5, v250, 6
	s_waitcnt vmcnt(0)
	v_add_u32_e32 v16, v16, v11
	s_nop 2
	global_load_dword v12, v157, s[4:5] sc1
	v_readlane_b32 s4, v250, 7
	v_readlane_b32 s5, v250, 8
	s_waitcnt vmcnt(0)
	v_add_u32_e32 v16, v16, v12
	s_nop 2
	global_load_dword v13, v157, s[4:5] sc1
	v_readlane_b32 s4, v250, 9
	v_readlane_b32 s5, v250, 10
	s_nop 4
	global_load_dword v14, v157, s[4:5] sc1
	global_load_dword v15, v157, s[84:85] sc1
	s_mov_b64 s[4:5], -1
	s_waitcnt vmcnt(2)
	v_add_u32_e32 v16, v16, v13
	s_waitcnt vmcnt(1)
	v_add_u32_e32 v16, v16, v14
	s_waitcnt vmcnt(0)
	v_add_u32_e32 v16, v16, v15
	v_cmp_eq_u32_e32 vcc, s62, v16
	s_cbranch_vccnz .LBB0_371
	s_and_b32 s4, s10, 0xff
	s_cmp_eq_u32 s4, 0
	s_mov_b64 s[4:5], -1
	s_mov_b64 s[8:9], -1
	s_nop 0
	s_cbranch_scc0 .LBB0_376
	global_load_dword v16, v157, s[88:89] sc1
	s_waitcnt vmcnt(0)
	v_cmp_eq_u32_e32 vcc, 0, v16
	s_cbranch_vccnz .LBB0_378
	s_mov_b64 s[8:9], 0

.LBB0_752:
	v_readlane_b32 s4, v249, 53
	v_readlane_b32 s5, v249, 54
	global_load_dword v3, v157, s[50:51] sc1
	s_waitcnt lgkmcnt(0)
	global_load_dword v0, v157, s[48:49] sc1
	global_load_dword v1, v157, s[52:53] sc1
	global_load_dword v2, v157, s[22:23] sc1
	s_mov_b64 s[6:7], -1
	global_load_dword v4, v157, s[4:5] sc1
	v_readlane_b32 s4, v249, 55
	v_readlane_b32 s5, v249, 56
	s_waitcnt vmcnt(3)
	v_add_u32_e32 v16, v0, v3
	s_nop 2
	global_load_dword v5, v157, s[4:5] sc1
	v_readlane_b32 s4, v249, 57
	v_readlane_b32 s5, v249, 58
	s_waitcnt vmcnt(3)
	v_add_u32_e32 v16, v16, v1
	s_waitcnt vmcnt(2)
	v_add_u32_e32 v16, v16, v2
	s_waitcnt vmcnt(1)
	v_add_u32_e32 v16, v16, v4
	s_waitcnt vmcnt(0)
	v_add_u32_e32 v16, v16, v5
	global_load_dword v6, v157, s[4:5] sc1
	v_readlane_b32 s4, v249, 59
	v_readlane_b32 s5, v249, 60
	s_waitcnt vmcnt(0)
	v_add_u32_e32 v16, v16, v6
	s_nop 2
	global_load_dword v7, v157, s[4:5] sc1
	v_readlane_b32 s4, v249, 61
	v_readlane_b32 s5, v249, 62
	s_waitcnt vmcnt(0)
	v_add_u32_e32 v16, v16, v7
	s_nop 2
	global_load_dword v8, v157, s[4:5] sc1
	v_readlane_b32 s4, v249, 63
	v_readlane_b32 s5, v250, 0
	s_waitcnt vmcnt(0)
	v_add_u32_e32 v16, v16, v8
	s_nop 2
	global_load_dword v9, v157, s[4:5] sc1
	v_readlane_b32 s4, v250, 1
	v_readlane_b32 s5, v250, 2
	s_waitcnt vmcnt(0)
	v_add_u32_e32 v16, v16, v9
	s_nop 2
	global_load_dword v10, v157, s[4:5] sc1
	v_readlane_b32 s4, v250, 3
	v_readlane_b32 s5, v250, 4
	s_waitcnt vmcnt(0)
	v_add_u32_e32 v16, v16, v10
	s_nop 2
	global_load_dword v11, v157, s[4:5] sc1
	v_readlane_b32 s4, v250, 5
	v_readlane_b32 s5, v250, 6
	s_waitcnt vmcnt(0)
	v_add_u32_e32 v16, v16, v11
	s_nop 2
	global_load_dword v12, v157, s[4:5] sc1
	v_readlane_b32 s4, v250, 7
	v_readlane_b32 s5, v250, 8
	s_waitcnt vmcnt(0)
	v_add_u32_e32 v16, v16, v12
	s_nop 2
	global_load_dword v13, v157, s[4:5] sc1
	v_readlane_b32 s4, v250, 9
	v_readlane_b32 s5, v250, 10
	s_nop 4
	global_load_dword v14, v157, s[4:5] sc1
	global_load_dword v15, v157, s[84:85] sc1
	s_mov_b64 s[4:5], -1
	s_waitcnt vmcnt(2)
	v_add_u32_e32 v16, v16, v13
	s_waitcnt vmcnt(1)
	v_add_u32_e32 v16, v16, v14
	s_waitcnt vmcnt(0)
	v_add_u32_e32 v16, v16, v15
	v_cmp_eq_u32_e32 vcc, s11, v16
	s_cbranch_vccnz .LBB0_751
	s_and_b32 s4, s10, 0xff
	s_cmp_eq_u32 s4, 0
	s_mov_b64 s[4:5], -1
	s_mov_b64 s[8:9], -1
	s_nop 0
	s_cbranch_scc0 .LBB0_756
	global_load_dword v16, v157, s[88:89] sc1
	s_waitcnt vmcnt(0)
	v_cmp_eq_u32_e32 vcc, 0, v16
	s_cbranch_vccnz .LBB0_758
	s_mov_b64 s[8:9], 0

.LBB0_850:
	v_readlane_b32 s4, v249, 53
	v_readlane_b32 s5, v249, 54
	global_load_dword v3, v157, s[50:51] sc1
	s_waitcnt lgkmcnt(0)
	global_load_dword v0, v157, s[48:49] sc1
	global_load_dword v1, v157, s[52:53] sc1
	global_load_dword v2, v157, s[56:57] sc1
	s_mov_b64 s[6:7], -1
	global_load_dword v4, v157, s[4:5] sc1
	v_readlane_b32 s4, v249, 55
	v_readlane_b32 s5, v249, 56
	s_waitcnt vmcnt(3)
	v_add_u32_e32 v16, v0, v3
	s_nop 2
	global_load_dword v5, v157, s[4:5] sc1
	v_readlane_b32 s4, v249, 57
	v_readlane_b32 s5, v249, 58
	s_waitcnt vmcnt(3)
	v_add_u32_e32 v16, v16, v1
	s_waitcnt vmcnt(2)
	v_add_u32_e32 v16, v16, v2
	s_waitcnt vmcnt(1)
	v_add_u32_e32 v16, v16, v4
	s_waitcnt vmcnt(0)
	v_add_u32_e32 v16, v16, v5
	global_load_dword v6, v157, s[4:5] sc1
	v_readlane_b32 s4, v249, 59
	v_readlane_b32 s5, v249, 60
	s_waitcnt vmcnt(0)
	v_add_u32_e32 v16, v16, v6
	s_nop 2
	global_load_dword v7, v157, s[4:5] sc1
	v_readlane_b32 s4, v249, 61
	v_readlane_b32 s5, v249, 62
	s_waitcnt vmcnt(0)
	v_add_u32_e32 v16, v16, v7
	s_nop 2
	global_load_dword v8, v157, s[4:5] sc1
	v_readlane_b32 s4, v249, 63
	v_readlane_b32 s5, v250, 0
	s_waitcnt vmcnt(0)
	v_add_u32_e32 v16, v16, v8
	s_nop 2
	global_load_dword v9, v157, s[4:5] sc1
	v_readlane_b32 s4, v250, 1
	v_readlane_b32 s5, v250, 2
	s_waitcnt vmcnt(0)
	v_add_u32_e32 v16, v16, v9
	s_nop 2
	global_load_dword v10, v157, s[4:5] sc1
	v_readlane_b32 s4, v250, 3
	v_readlane_b32 s5, v250, 4
	s_waitcnt vmcnt(0)
	v_add_u32_e32 v16, v16, v10
	s_nop 2
	global_load_dword v11, v157, s[4:5] sc1
	v_readlane_b32 s4, v250, 5
	v_readlane_b32 s5, v250, 6
	s_waitcnt vmcnt(0)
	v_add_u32_e32 v16, v16, v11
	s_nop 2
	global_load_dword v12, v157, s[4:5] sc1
	v_readlane_b32 s4, v250, 7
	v_readlane_b32 s5, v250, 8
	s_waitcnt vmcnt(0)
	v_add_u32_e32 v16, v16, v12
	s_nop 2
	global_load_dword v13, v157, s[4:5] sc1
	v_readlane_b32 s4, v250, 9
	v_readlane_b32 s5, v250, 10
	s_nop 4
	global_load_dword v14, v157, s[4:5] sc1
	global_load_dword v15, v157, s[84:85] sc1
	s_mov_b64 s[4:5], -1
	s_waitcnt vmcnt(2)
	v_add_u32_e32 v16, v16, v13
	s_waitcnt vmcnt(1)
	v_add_u32_e32 v16, v16, v14
	s_waitcnt vmcnt(0)
	v_add_u32_e32 v16, v16, v15
	v_cmp_eq_u32_e32 vcc, s62, v16
	s_cbranch_vccnz .LBB0_849
	s_and_b32 s4, s10, 0xff
	s_cmp_eq_u32 s4, 0
	s_mov_b64 s[4:5], -1
	s_mov_b64 s[8:9], -1
	s_nop 0
	s_cbranch_scc0 .LBB0_854
	global_load_dword v16, v157, s[88:89] sc1
	s_waitcnt vmcnt(0)
	v_cmp_eq_u32_e32 vcc, 0, v16
	s_cbranch_vccnz .LBB0_856
	s_mov_b64 s[8:9], 0
